# P6 final-norm exchange: tagged slots polled directly, counter + drain removed (on top of v17)
# speedup vs baseline: 1.0111x; 1.0023x over previous
;     __device__ __forceinline__ bool run(const f32x4 (&v)[2][2][4][2], const Unit& u, int wr, int wc, int fr, int fq, PG8_LAS unsigned char* lds, int wid, int lane) const {
;     ...
;         asm volatile("s_waitcnt vmcnt(0)" ::: "memory");
;         if (lane == 0) __hip_atomic_fetch_add(cnt + 64 * u.pm, 1u, __ATOMIC_RELAXED, __HIP_MEMORY_SCOPE_AGENT);
;         if (wid == 0) {
;             bool dead = false; const unsigned long long t0 = __builtin_amdgcn_s_memrealtime(); const unsigned want = 8u * (unsigned)ntn;
;             for (;;) {
;                 if ((unsigned)__builtin_amdgcn_readfirstlane(__hip_atomic_load(cnt + 64 * u.pm, __ATOMIC_RELAXED, __HIP_MEMORY_SCOPE_AGENT)) >= want) break;
;                 if (__builtin_amdgcn_s_memrealtime() - t0 > 2000000ull) {
;                     if (lane == 0) { unsigned expect = 0u; __hip_atomic_compare_exchange_strong(tmo + 1, &expect, code | (unsigned)(u.pm & 0xff), __ATOMIC_RELAXED, __ATOMIC_RELAXED, __HIP_MEMORY_SCOPE_AGENT);
;                                      __hip_atomic_store(tmo, 1u, __ATOMIC_RELAXED, __HIP_MEMORY_SCOPE_AGENT); }
;                     dead = true; break; }
;                 __builtin_amdgcn_s_sleep(2);
;             }
;             if (lane == 0) flag[0] = dead ? 1u : 0u;
;         }
;         asm volatile("s_waitcnt vmcnt(0) lgkmcnt(0)" ::: "memory"); __builtin_amdgcn_s_barrier(); asm volatile("" ::: "memory");
;         const bool bad = flag[0] != 0u;
;         if (lane < 32) {
;             const unsigned long long* slot = (const unsigned long long*)xbuf + (size_t)(u.pm * BM + row) * 4; float q = 0.f;
; #pragma unroll
;             for (int t = 0; t < 4; ++t) if (t < ntn) { const unsigned long long w = __hip_atomic_load(slot + t, __ATOMIC_RELAXED, __HIP_MEMORY_SCOPE_AGENT); q += __uint_as_float((unsigned)w); }
;             S[row] = 1.0f / sqrtf(q / (256.0f * (float)ntn) + eps);
.LBB0_1012:
	s_or_b64 exec, exec, s[2:3]
	v_readlane_b32 s6, v252, 11
	v_readlane_b32 s7, v252, 12
	s_nop 1
	s_andn2_b64 vcc, exec, s[6:7]
	s_cbranch_vccnz .LBB0_1031
	v_cmp_eq_u32_e32 vcc, 0, v150
	s_and_saveexec_b64 s[10:11], vcc
	v_mov_b32_e32 v130, 0
	ds_write_b32 v130, v130 offset:10240
	s_or_b64 exec, exec, s[10:11]
.LBB0_1031:
	s_waitcnt lgkmcnt(0)
	s_barrier
	v_mov_b32_e32 v130, 0
	ds_read_b32 v140, v130 offset:10240
	s_and_saveexec_b64 s[2:3], s[0:1]
	s_cbranch_execz .LBB0_1033
	v_lshlrev_b64 v[128:129], 5, v[128:129]
	v_lshl_add_u64 v[128:129], s[8:9], 0, v[128:129]
	s_mov_b32 s6, 0
.Lp6_poll:
	global_load_dwordx2 v[130:131], v[128:129], off sc1
	global_load_dwordx2 v[134:135], v[128:129], off offset:8 sc1
	global_load_dwordx2 v[136:137], v[128:129], off offset:16 sc1
	global_load_dwordx2 v[138:139], v[128:129], off offset:24 sc1
	s_waitcnt vmcnt(0)
	v_xor_b32_e32 v131, 1, v131
	v_xor_b32_e32 v135, 1, v135
	v_xor_b32_e32 v137, 1, v137
	v_xor_b32_e32 v139, 1, v139
	v_or3_b32 v131, v131, v135, v137
	v_or_b32_e32 v131, v131, v139
	v_cmp_ne_u32_e32 vcc, 0, v131
	s_cbranch_vccz .Lp6_ready
	s_add_i32 s6, s6, 1
	s_cmp_lt_u32 s6, 0x40000
	s_cbranch_scc0 .Lp6_giveup
	s_sleep 1
	s_branch .Lp6_poll
.Lp6_giveup:
	v_mov_b32_e32 v130, 0x7fc00000
.Lp6_ready:
	v_mov_b32_e32 v128, v138
	v_mov_b32_e32 v129, 0x358637bd
	s_mov_b32 s0, 0xf800000
	v_add_f32_e32 v130, 0, v130
	v_add_f32_e32 v130, v130, v134
	v_add_f32_e32 v130, v130, v136
	v_add_f32_e32 v128, v130, v128
	v_fmac_f32_e32 v129, 0x3a800000, v128
	v_mul_f32_e32 v128, 0x4f800000, v129
	v_cmp_gt_f32_e32 vcc, s0, v129
	v_mov_b32_e32 v130, 0x260
	s_nop 0
	v_cndmask_b32_e32 v128, v129, v128, vcc
	v_sqrt_f32_e32 v129, v128
	s_nop 0
	v_add_u32_e32 v131, -1, v129
	v_add_u32_e32 v133, 1, v129
	v_fma_f32 v134, -v131, v129, v128
	v_fma_f32 v135, -v133, v129, v128
	v_cmp_ge_f32_e64 s[0:1], 0, v134
	s_nop 1
	v_cndmask_b32_e64 v129, v129, v131, s[0:1]
	v_cmp_lt_f32_e64 s[0:1], 0, v135
	s_nop 1
	v_cndmask_b32_e64 v129, v129, v133, s[0:1]
	v_mul_f32_e32 v131, 0x37800000, v129
	v_cndmask_b32_e32 v129, v129, v131, vcc
	v_cmp_class_f32_e32 vcc, v128, v130
	s_nop 1
	v_cndmask_b32_e32 v128, v129, v128, vcc
	v_div_scale_f32 v129, s[0:1], v128, v128, 1.0
	v_rcp_f32_e32 v130, v129
	v_div_scale_f32 v131, vcc, 1.0, v128, 1.0
	v_fma_f32 v133, -v129, v130, 1.0
	v_fmac_f32_e32 v130, v133, v130
	v_mul_f32_e32 v133, v131, v130
	v_fma_f32 v134, -v129, v133, v131
	v_fmac_f32_e32 v133, v134, v130
	v_fma_f32 v129, -v129, v133, v131
	v_div_fmas_f32 v129, v129, v130, v133
	v_div_fixup_f32 v128, v129, v128, 1.0
	v_lshl_add_u32 v129, v132, 2, 0
	ds_write_b32 v129, v128 offset:8192
